# o30 + last 8 K-blocks of the FFN2 gate/up conversion (LN2 fold) moved from the filler queue to the GU1 idle tail (hand-written fold converter, v66-129 parked in LDS)
# baseline (speedup 1.0000x reference)
.Lw1d_go:
	v_lshlrev_b32_e32 v2, 4, v0
	v_add_u32_e32 v3, 0x10000, v2
	ds_write_b128 v2, v[66:69] offset:0
	ds_write_b128 v2, v[70:73] offset:8192
	ds_write_b128 v2, v[74:77] offset:16384
	ds_write_b128 v2, v[78:81] offset:24576
	ds_write_b128 v2, v[82:85] offset:32768
	ds_write_b128 v2, v[86:89] offset:40960
	ds_write_b128 v2, v[90:93] offset:49152
	ds_write_b128 v2, v[94:97] offset:57344
	ds_write_b128 v3, v[98:101] offset:0
	ds_write_b128 v3, v[102:105] offset:8192
	ds_write_b128 v3, v[106:109] offset:16384
	ds_write_b128 v3, v[110:113] offset:24576
	ds_write_b128 v3, v[114:117] offset:32768
	ds_write_b128 v3, v[118:121] offset:40960
	ds_write_b128 v3, v[122:125] offset:49152
	ds_write_b128 v3, v[126:129] offset:57344
	v_readlane_b32 s0, v253, 21
	v_readlane_b32 s1, v253, 22
	s_nop 3
	s_sub_u32 s0, s0, 0xe0
	s_subb_u32 s1, s1, 0
	s_load_dwordx2 s[8:9], s[0:1], 0x50
	s_load_dwordx2 s[10:11], s[0:1], 0x90
	s_load_dwordx8 s[56:63], s[0:1], 0x98
	s_add_u32 s64, s86, 0x54000
	s_addc_u32 s65, s87, 0
	s_add_u32 s66, s86, 0x60000
	s_addc_u32 s67, s87, 0
	s_add_u32 s68, s86, 0x8c60200
	s_addc_u32 s69, s87, 0
	s_add_u32 s6, s86, 0xc600
	s_addc_u32 s7, s87, 0
	v_and_b32_e32 v6, 15, v0
	v_and_b32_e32 v7, 48, v0
	v_lshlrev_b32_e32 v8, 13, v7
	v_lshl_or_b32 v8, v6, 4, v8
	v_lshlrev_b32_e32 v9, 2, v6
	v_and_b32_e32 v9, 32, v9
	v_lshlrev_b32_e32 v10, 4, v6
	v_and_b32_e32 v10, 16, v10
	v_lshlrev_b32_e32 v11, 1, v6
	v_and_b32_e32 v11, 12, v11
	v_or3_b32 v9, v9, v10, v11
	v_lshlrev_b32_e32 v44, 12, v9
	v_lshl_add_u32 v44, v7, 1, v44
	v_add_u32_e32 v45, 0x1000, v44
	v_add_u32_e32 v46, 0x2000, v44
	v_add_u32_e32 v47, 0x3000, v44
	v_mul_u32_u24_e32 v9, 0x2c00, v9
	v_lshl_add_u32 v12, v7, 1, v9
	v_add_u32_e32 v13, 0x2c00, v12
	v_add_u32_e32 v14, 0x5800, v12
	v_add_u32_e32 v15, 0x8400, v12
	s_waitcnt lgkmcnt(0)
	v_mul_u32_u24_e32 v124, 0x5800, v7
	v_lshl_add_u32 v124, v6, 4, v124
	v_lshlrev_b32_e32 v125, 2, v6
	v_lshlrev_b32_e32 v126, 2, v7
	v_and_b32_e32 v19, 63, v0
	v_xor_b32_e32 v48, 16, v19
	v_lshlrev_b32_e32 v48, 2, v48
	v_xor_b32_e32 v1, 32, v19
	v_lshlrev_b32_e32 v1, 2, v1
	v_cmp_gt_u32_e64 s[36:37], 16, v19
	v_mov_b32_e32 v16, 0
	v_mov_b32_e32 v17, 1
	s_mov_b64 exec, 1
	global_atomic_add v18, v16, v17, s[6:7] sc0
	s_mov_b64 exec, -1
	s_waitcnt vmcnt(0) lgkmcnt(0)
.Lw1d_loop:
	v_readfirstlane_b32 s98, v18
	s_nop 3
	s_cmpk_ge_u32 s98, 0xa40
	s_cbranch_scc1 .Lw1d_rest
	s_cmpk_ge_u32 s98, 0x780
	s_cbranch_scc1 .Lw2t_item
	s_cmpk_ge_u32 s98, 0x580
	s_cbranch_scc1 .Lwo_item
	s_lshr_b32 s99, s98, 4
	s_and_b32 s100, s98, 15
	s_lshl_b32 s101, s99, 19
	s_lshl_b32 s0, s100, 9
	s_add_u32 s0, s0, s101
	s_add_u32 s0, s8, s0
	s_addc_u32 s1, s9, 0
	s_mul_i32 s2, s100, 0x160000
	s_lshl_b32 s3, s99, 7
	s_add_u32 s2, s2, s3
	s_add_u32 s2, s2, 0x2d60200
	s_add_u32 s2, s86, s2
	s_addc_u32 s3, s87, 0
	s_add_u32 s4, s2, 0xb0000
	s_addc_u32 s5, s3, 0
	global_load_dwordx4 v[154:157], v8, s[0:1] nt
	global_load_dwordx4 v[204:207], v8, s[0:1] offset:256 nt
	s_add_u32 s0, s0, 0x2000
	s_addc_u32 s1, s1, 0
	global_load_dwordx4 v[158:161], v8, s[0:1] nt
	global_load_dwordx4 v[208:211], v8, s[0:1] offset:256 nt
	s_add_u32 s0, s0, 0x2000
	s_addc_u32 s1, s1, 0
	global_load_dwordx4 v[162:165], v8, s[0:1] nt
	global_load_dwordx4 v[212:215], v8, s[0:1] offset:256 nt
	s_add_u32 s0, s0, 0x2000
	s_addc_u32 s1, s1, 0
	global_load_dwordx4 v[166:169], v8, s[0:1] nt
	global_load_dwordx4 v[216:219], v8, s[0:1] offset:256 nt
	s_add_u32 s0, s0, 0x2000
	s_addc_u32 s1, s1, 0
	global_load_dwordx4 v[170:173], v8, s[0:1] nt
	global_load_dwordx4 v[220:223], v8, s[0:1] offset:256 nt
	s_add_u32 s0, s0, 0x2000
	s_addc_u32 s1, s1, 0
	global_load_dwordx4 v[174:177], v8, s[0:1] nt
	global_load_dwordx4 v[224:227], v8, s[0:1] offset:256 nt
	s_add_u32 s0, s0, 0x2000
	s_addc_u32 s1, s1, 0
	global_load_dwordx4 v[178:181], v8, s[0:1] nt
	global_load_dwordx4 v[228:231], v8, s[0:1] offset:256 nt
	s_add_u32 s0, s0, 0x2000
	s_addc_u32 s1, s1, 0
	global_load_dwordx4 v[182:185], v8, s[0:1] nt
	global_load_dwordx4 v[232:235], v8, s[0:1] offset:256 nt
	s_add_u32 s0, s0, 0x2000
	s_addc_u32 s1, s1, 0
	global_load_dwordx4 v[186:189], v8, s[0:1] nt
	global_load_dwordx4 v[236:239], v8, s[0:1] offset:256 nt
	s_add_u32 s0, s0, 0x2000
	s_addc_u32 s1, s1, 0
	global_load_dwordx4 v[190:193], v8, s[0:1] nt
	global_load_dwordx4 v[240:243], v8, s[0:1] offset:256 nt
	s_add_u32 s0, s0, 0x2000
	s_addc_u32 s1, s1, 0
	global_load_dwordx4 v[194:197], v8, s[0:1] nt
	global_load_dwordx4 v[244:247], v8, s[0:1] offset:256 nt
	s_add_u32 s0, s0, 0x2000
	s_addc_u32 s1, s1, 0
	global_load_dwordx4 v[198:201], v8, s[0:1] nt
	global_load_dwordx4 v[248:251], v8, s[0:1] offset:256 nt
	s_add_u32 s0, s0, 0x2000
	s_addc_u32 s1, s1, 0
	global_load_dwordx4 v[130:133], v8, s[0:1] nt
	global_load_dwordx4 v[50:53], v8, s[0:1] offset:256 nt
	s_add_u32 s0, s0, 0x2000
	s_addc_u32 s1, s1, 0
	global_load_dwordx4 v[134:137], v8, s[0:1] nt
	global_load_dwordx4 v[54:57], v8, s[0:1] offset:256 nt
	s_add_u32 s0, s0, 0x2000
	s_addc_u32 s1, s1, 0
	global_load_dwordx4 v[138:141], v8, s[0:1] nt
	global_load_dwordx4 v[58:61], v8, s[0:1] offset:256 nt
	s_add_u32 s0, s0, 0x2000
	s_addc_u32 s1, s1, 0
	global_load_dwordx4 v[142:145], v8, s[0:1] nt
	global_load_dwordx4 v[62:65], v8, s[0:1] offset:256 nt
	s_mov_b64 exec, 1
	global_atomic_add v18, v16, v17, s[6:7] sc0
	s_mov_b64 exec, -1
	s_waitcnt vmcnt(1)
	v_cvt_pk_bf16_f32 v20, v154, v158
	v_cvt_pk_bf16_f32 v21, v162, v166
	v_cvt_pk_bf16_f32 v22, v170, v174
	v_cvt_pk_bf16_f32 v23, v178, v182
	global_store_dwordx4 v12, v[20:23], s[2:3]
	v_cvt_pk_bf16_f32 v24, v186, v190
	v_cvt_pk_bf16_f32 v25, v194, v198
	v_cvt_pk_bf16_f32 v26, v130, v134
	v_cvt_pk_bf16_f32 v27, v138, v142
	global_store_dwordx4 v12, v[24:27], s[2:3] offset:16
	v_cvt_pk_bf16_f32 v28, v155, v159
	v_cvt_pk_bf16_f32 v29, v163, v167
	v_cvt_pk_bf16_f32 v30, v171, v175
	v_cvt_pk_bf16_f32 v31, v179, v183
	global_store_dwordx4 v13, v[28:31], s[2:3]
	v_cvt_pk_bf16_f32 v32, v187, v191
	v_cvt_pk_bf16_f32 v33, v195, v199
	v_cvt_pk_bf16_f32 v34, v131, v135
	v_cvt_pk_bf16_f32 v35, v139, v143
	global_store_dwordx4 v13, v[32:35], s[2:3] offset:16
	v_cvt_pk_bf16_f32 v36, v156, v160
	v_cvt_pk_bf16_f32 v37, v164, v168
	v_cvt_pk_bf16_f32 v38, v172, v176
	v_cvt_pk_bf16_f32 v39, v180, v184
	global_store_dwordx4 v14, v[36:39], s[2:3]
	v_cvt_pk_bf16_f32 v40, v188, v192
	v_cvt_pk_bf16_f32 v41, v196, v200
	v_cvt_pk_bf16_f32 v42, v132, v136
	v_cvt_pk_bf16_f32 v43, v140, v144
	global_store_dwordx4 v14, v[40:43], s[2:3] offset:16
	v_cvt_pk_bf16_f32 v20, v157, v161
	v_cvt_pk_bf16_f32 v21, v165, v169
	v_cvt_pk_bf16_f32 v22, v173, v177
	v_cvt_pk_bf16_f32 v23, v181, v185
	global_store_dwordx4 v15, v[20:23], s[2:3]
	v_cvt_pk_bf16_f32 v24, v189, v193
	v_cvt_pk_bf16_f32 v25, v197, v201
	v_cvt_pk_bf16_f32 v26, v133, v137
	v_cvt_pk_bf16_f32 v27, v141, v145
	global_store_dwordx4 v15, v[24:27], s[2:3] offset:16
	v_cvt_pk_bf16_f32 v28, v204, v208
	v_cvt_pk_bf16_f32 v29, v212, v216
	v_cvt_pk_bf16_f32 v30, v220, v224
	v_cvt_pk_bf16_f32 v31, v228, v232
	global_store_dwordx4 v12, v[28:31], s[4:5]
	v_cvt_pk_bf16_f32 v32, v236, v240
	v_cvt_pk_bf16_f32 v33, v244, v248
	v_cvt_pk_bf16_f32 v34, v50, v54
	v_cvt_pk_bf16_f32 v35, v58, v62
	global_store_dwordx4 v12, v[32:35], s[4:5] offset:16
	v_cvt_pk_bf16_f32 v36, v205, v209
	v_cvt_pk_bf16_f32 v37, v213, v217
	v_cvt_pk_bf16_f32 v38, v221, v225
	v_cvt_pk_bf16_f32 v39, v229, v233
	global_store_dwordx4 v13, v[36:39], s[4:5]
	v_cvt_pk_bf16_f32 v40, v237, v241
	v_cvt_pk_bf16_f32 v41, v245, v249
	v_cvt_pk_bf16_f32 v42, v51, v55
	v_cvt_pk_bf16_f32 v43, v59, v63
	global_store_dwordx4 v13, v[40:43], s[4:5] offset:16
	v_cvt_pk_bf16_f32 v20, v206, v210
	v_cvt_pk_bf16_f32 v21, v214, v218
	v_cvt_pk_bf16_f32 v22, v222, v226
	v_cvt_pk_bf16_f32 v23, v230, v234
	global_store_dwordx4 v14, v[20:23], s[4:5]
	v_cvt_pk_bf16_f32 v24, v238, v242
	v_cvt_pk_bf16_f32 v25, v246, v250
	v_cvt_pk_bf16_f32 v26, v52, v56
	v_cvt_pk_bf16_f32 v27, v60, v64
	global_store_dwordx4 v14, v[24:27], s[4:5] offset:16
	v_cvt_pk_bf16_f32 v28, v207, v211
	v_cvt_pk_bf16_f32 v29, v215, v219
	v_cvt_pk_bf16_f32 v30, v223, v227
	v_cvt_pk_bf16_f32 v31, v231, v235
	global_store_dwordx4 v15, v[28:31], s[4:5]
	v_cvt_pk_bf16_f32 v32, v239, v243
	v_cvt_pk_bf16_f32 v33, v247, v251
	v_cvt_pk_bf16_f32 v34, v53, v57
	v_cvt_pk_bf16_f32 v35, v61, v65
	global_store_dwordx4 v15, v[32:35], s[4:5] offset:16
	s_waitcnt vmcnt(16)
	s_branch .Lw1d_loop

.Lw2t_item:
	s_sub_u32 s98, s98, 0x780
	s_lshl_b32 s99, s98, 1
	s_add_u32 s99, s99, 0x1080
	s_mul_i32 s100, s99, 0xba2f
	s_lshr_b32 s100, s100, 23
	s_mul_i32 s101, s100, 0xb0
	s_sub_u32 s101, s99, s101
	s_and_b32 s70, s101, 2
	s_cmp_eq_u32 s70, 0
	s_cselect_b32 s72, s60, s62
	s_cselect_b32 s73, s61, s63
	s_lshr_b32 s70, s101, 2
	s_lshl_b32 s70, s70, 9
	s_mul_i32 s71, s100, 0x160000
	s_add_u32 s70, s70, s71
	s_add_u32 s0, s72, s70
	s_addc_u32 s1, s73, 0
	s_lshl_b32 s70, s101, 18
	s_lshl_b32 s71, s100, 7
	s_add_u32 s70, s70, s71
	s_add_u32 s2, s68, s70
	s_addc_u32 s3, s69, 0
	s_add_u32 s4, s2, 0x40000
	s_addc_u32 s5, s3, 0
	s_lshl_b32 s70, s101, 8
	s_add_u32 s72, s64, s70
	s_addc_u32 s73, s65, 0
	s_add_u32 s74, s66, s70
	s_addc_u32 s75, s67, 0
	s_add_u32 s76, s72, 0x100
	s_addc_u32 s77, s73, 0
	s_add_u32 s78, s74, 0x100
	s_addc_u32 s79, s75, 0
	s_lshl_b32 s70, s100, 8
	s_add_u32 s32, s56, s70
	s_addc_u32 s33, s57, 0
	s_add_u32 s34, s58, s70
	s_addc_u32 s35, s59, 0
	global_load_dwordx4 v[66:69], v126, s[32:33] offset:0
	global_load_dwordx4 v[82:85], v126, s[34:35] offset:0
	global_load_dwordx4 v[70:73], v126, s[32:33] offset:16
	global_load_dwordx4 v[86:89], v126, s[34:35] offset:16
	global_load_dwordx4 v[74:77], v126, s[32:33] offset:32
	global_load_dwordx4 v[90:93], v126, s[34:35] offset:32
	global_load_dwordx4 v[78:81], v126, s[32:33] offset:48
	global_load_dwordx4 v[94:97], v126, s[34:35] offset:48
	global_load_dwordx4 v[154:157], v124, s[0:1] nt
	global_load_dwordx4 v[204:207], v124, s[0:1] offset:256 nt
	s_add_u32 s0, s0, 0x5800
	s_addc_u32 s1, s1, 0
	global_load_dwordx4 v[158:161], v124, s[0:1] nt
	global_load_dwordx4 v[208:211], v124, s[0:1] offset:256 nt
	s_add_u32 s0, s0, 0x5800
	s_addc_u32 s1, s1, 0
	global_load_dwordx4 v[162:165], v124, s[0:1] nt
	global_load_dwordx4 v[212:215], v124, s[0:1] offset:256 nt
	s_add_u32 s0, s0, 0x5800
	s_addc_u32 s1, s1, 0
	global_load_dwordx4 v[166:169], v124, s[0:1] nt
	global_load_dwordx4 v[216:219], v124, s[0:1] offset:256 nt
	s_add_u32 s0, s0, 0x5800
	s_addc_u32 s1, s1, 0
	global_load_dwordx4 v[170:173], v124, s[0:1] nt
	global_load_dwordx4 v[220:223], v124, s[0:1] offset:256 nt
	s_add_u32 s0, s0, 0x5800
	s_addc_u32 s1, s1, 0
	global_load_dwordx4 v[174:177], v124, s[0:1] nt
	global_load_dwordx4 v[224:227], v124, s[0:1] offset:256 nt
	s_add_u32 s0, s0, 0x5800
	s_addc_u32 s1, s1, 0
	global_load_dwordx4 v[178:181], v124, s[0:1] nt
	global_load_dwordx4 v[228:231], v124, s[0:1] offset:256 nt
	s_add_u32 s0, s0, 0x5800
	s_addc_u32 s1, s1, 0
	global_load_dwordx4 v[182:185], v124, s[0:1] nt
	global_load_dwordx4 v[232:235], v124, s[0:1] offset:256 nt
	s_add_u32 s0, s0, 0x5800
	s_addc_u32 s1, s1, 0
	global_load_dwordx4 v[186:189], v124, s[0:1] nt
	global_load_dwordx4 v[236:239], v124, s[0:1] offset:256 nt
	s_add_u32 s0, s0, 0x5800
	s_addc_u32 s1, s1, 0
	global_load_dwordx4 v[190:193], v124, s[0:1] nt
	global_load_dwordx4 v[240:243], v124, s[0:1] offset:256 nt
	s_add_u32 s0, s0, 0x5800
	s_addc_u32 s1, s1, 0
	global_load_dwordx4 v[194:197], v124, s[0:1] nt
	global_load_dwordx4 v[244:247], v124, s[0:1] offset:256 nt
	s_add_u32 s0, s0, 0x5800
	s_addc_u32 s1, s1, 0
	global_load_dwordx4 v[198:201], v124, s[0:1] nt
	global_load_dwordx4 v[248:251], v124, s[0:1] offset:256 nt
	s_add_u32 s0, s0, 0x5800
	s_addc_u32 s1, s1, 0
	global_load_dwordx4 v[130:133], v124, s[0:1] nt
	global_load_dwordx4 v[50:53], v124, s[0:1] offset:256 nt
	s_add_u32 s0, s0, 0x5800
	s_addc_u32 s1, s1, 0
	global_load_dwordx4 v[134:137], v124, s[0:1] nt
	global_load_dwordx4 v[54:57], v124, s[0:1] offset:256 nt
	s_add_u32 s0, s0, 0x5800
	s_addc_u32 s1, s1, 0
	global_load_dwordx4 v[138:141], v124, s[0:1] nt
	global_load_dwordx4 v[58:61], v124, s[0:1] offset:256 nt
	s_add_u32 s0, s0, 0x5800
	s_addc_u32 s1, s1, 0
	global_load_dwordx4 v[142:145], v124, s[0:1] nt
	global_load_dwordx4 v[62:65], v124, s[0:1] offset:256 nt
	s_mov_b64 exec, 1
	global_atomic_add v18, v16, v17, s[6:7] sc0
	s_mov_b64 exec, -1
	s_waitcnt vmcnt(1)
	v_mul_f32_e32 v98, v154, v82
	v_mul_f32_e32 v99, v155, v82
	v_mul_f32_e32 v100, v156, v82
	v_mul_f32_e32 v101, v157, v82
	v_mul_f32_e32 v154, v154, v66
	v_mul_f32_e32 v155, v155, v66
	v_mul_f32_e32 v156, v156, v66
	v_mul_f32_e32 v157, v157, v66
	v_fmac_f32_e32 v98, v158, v83
	v_fmac_f32_e32 v99, v159, v83
	v_fmac_f32_e32 v100, v160, v83
	v_fmac_f32_e32 v101, v161, v83
	v_mul_f32_e32 v158, v158, v67
	v_mul_f32_e32 v159, v159, v67
	v_mul_f32_e32 v160, v160, v67
	v_mul_f32_e32 v161, v161, v67
	v_fmac_f32_e32 v98, v162, v84
	v_fmac_f32_e32 v99, v163, v84
	v_fmac_f32_e32 v100, v164, v84
	v_fmac_f32_e32 v101, v165, v84
	v_mul_f32_e32 v162, v162, v68
	v_mul_f32_e32 v163, v163, v68
	v_mul_f32_e32 v164, v164, v68
	v_mul_f32_e32 v165, v165, v68
	v_fmac_f32_e32 v98, v166, v85
	v_fmac_f32_e32 v99, v167, v85
	v_fmac_f32_e32 v100, v168, v85
	v_fmac_f32_e32 v101, v169, v85
	v_mul_f32_e32 v166, v166, v69
	v_mul_f32_e32 v167, v167, v69
	v_mul_f32_e32 v168, v168, v69
	v_mul_f32_e32 v169, v169, v69
	v_fmac_f32_e32 v98, v170, v86
	v_fmac_f32_e32 v99, v171, v86
	v_fmac_f32_e32 v100, v172, v86
	v_fmac_f32_e32 v101, v173, v86
	v_mul_f32_e32 v170, v170, v70
	v_mul_f32_e32 v171, v171, v70
	v_mul_f32_e32 v172, v172, v70
	v_mul_f32_e32 v173, v173, v70
	v_fmac_f32_e32 v98, v174, v87
	v_fmac_f32_e32 v99, v175, v87
	v_fmac_f32_e32 v100, v176, v87
	v_fmac_f32_e32 v101, v177, v87
	v_mul_f32_e32 v174, v174, v71
	v_mul_f32_e32 v175, v175, v71
	v_mul_f32_e32 v176, v176, v71
	v_mul_f32_e32 v177, v177, v71
	v_fmac_f32_e32 v98, v178, v88
	v_fmac_f32_e32 v99, v179, v88
	v_fmac_f32_e32 v100, v180, v88
	v_fmac_f32_e32 v101, v181, v88
	v_mul_f32_e32 v178, v178, v72
	v_mul_f32_e32 v179, v179, v72
	v_mul_f32_e32 v180, v180, v72
	v_mul_f32_e32 v181, v181, v72
	v_fmac_f32_e32 v98, v182, v89
	v_fmac_f32_e32 v99, v183, v89
	v_fmac_f32_e32 v100, v184, v89
	v_fmac_f32_e32 v101, v185, v89
	v_mul_f32_e32 v182, v182, v73
	v_mul_f32_e32 v183, v183, v73
	v_mul_f32_e32 v184, v184, v73
	v_mul_f32_e32 v185, v185, v73
	v_fmac_f32_e32 v98, v186, v90
	v_fmac_f32_e32 v99, v187, v90
	v_fmac_f32_e32 v100, v188, v90
	v_fmac_f32_e32 v101, v189, v90
	v_mul_f32_e32 v186, v186, v74
	v_mul_f32_e32 v187, v187, v74
	v_mul_f32_e32 v188, v188, v74
	v_mul_f32_e32 v189, v189, v74
	v_fmac_f32_e32 v98, v190, v91
	v_fmac_f32_e32 v99, v191, v91
	v_fmac_f32_e32 v100, v192, v91
	v_fmac_f32_e32 v101, v193, v91
	v_mul_f32_e32 v190, v190, v75
	v_mul_f32_e32 v191, v191, v75
	v_mul_f32_e32 v192, v192, v75
	v_mul_f32_e32 v193, v193, v75
	v_fmac_f32_e32 v98, v194, v92
	v_fmac_f32_e32 v99, v195, v92
	v_fmac_f32_e32 v100, v196, v92
	v_fmac_f32_e32 v101, v197, v92
	v_mul_f32_e32 v194, v194, v76
	v_mul_f32_e32 v195, v195, v76
	v_mul_f32_e32 v196, v196, v76
	v_mul_f32_e32 v197, v197, v76
	v_fmac_f32_e32 v98, v198, v93
	v_fmac_f32_e32 v99, v199, v93
	v_fmac_f32_e32 v100, v200, v93
	v_fmac_f32_e32 v101, v201, v93
	v_mul_f32_e32 v198, v198, v77
	v_mul_f32_e32 v199, v199, v77
	v_mul_f32_e32 v200, v200, v77
	v_mul_f32_e32 v201, v201, v77
	v_fmac_f32_e32 v98, v130, v94
	v_fmac_f32_e32 v99, v131, v94
	v_fmac_f32_e32 v100, v132, v94
	v_fmac_f32_e32 v101, v133, v94
	v_mul_f32_e32 v130, v130, v78
	v_mul_f32_e32 v131, v131, v78
	v_mul_f32_e32 v132, v132, v78
	v_mul_f32_e32 v133, v133, v78
	v_fmac_f32_e32 v98, v134, v95
	v_fmac_f32_e32 v99, v135, v95
	v_fmac_f32_e32 v100, v136, v95
	v_fmac_f32_e32 v101, v137, v95
	v_mul_f32_e32 v134, v134, v79
	v_mul_f32_e32 v135, v135, v79
	v_mul_f32_e32 v136, v136, v79
	v_mul_f32_e32 v137, v137, v79
	v_fmac_f32_e32 v98, v138, v96
	v_fmac_f32_e32 v99, v139, v96
	v_fmac_f32_e32 v100, v140, v96
	v_fmac_f32_e32 v101, v141, v96
	v_mul_f32_e32 v138, v138, v80
	v_mul_f32_e32 v139, v139, v80
	v_mul_f32_e32 v140, v140, v80
	v_mul_f32_e32 v141, v141, v80
	v_fmac_f32_e32 v98, v142, v97
	v_fmac_f32_e32 v99, v143, v97
	v_fmac_f32_e32 v100, v144, v97
	v_fmac_f32_e32 v101, v145, v97
	v_mul_f32_e32 v142, v142, v81
	v_mul_f32_e32 v143, v143, v81
	v_mul_f32_e32 v144, v144, v81
	v_mul_f32_e32 v145, v145, v81
	v_lshlrev_b32_e32 v2, 2, v125
	v_lshlrev_b32_e32 v3, 12, v125
	v_lshl_add_u32 v3, v7, 1, v3
	ds_bpermute_b32 v106, v48, v98
	ds_bpermute_b32 v107, v48, v99
	ds_bpermute_b32 v108, v48, v100
	ds_bpermute_b32 v109, v48, v101
	s_waitcnt lgkmcnt(0)
	v_add_f32_e32 v98, v98, v106
	v_add_f32_e32 v99, v99, v107
	v_add_f32_e32 v100, v100, v108
	v_add_f32_e32 v101, v101, v109
	ds_bpermute_b32 v106, v1, v98
	ds_bpermute_b32 v107, v1, v99
	ds_bpermute_b32 v108, v1, v100
	ds_bpermute_b32 v109, v1, v101
	s_waitcnt lgkmcnt(0)
	v_add_f32_e32 v98, v98, v106
	v_add_f32_e32 v99, v99, v107
	v_add_f32_e32 v100, v100, v108
	v_add_f32_e32 v101, v101, v109
	s_mov_b64 exec, s[36:37]
	global_atomic_add_f32 v2, v98, s[74:75] offset:0
	global_atomic_add_f32 v2, v99, s[74:75] offset:4
	global_atomic_add_f32 v2, v100, s[74:75] offset:8
	global_atomic_add_f32 v2, v101, s[74:75] offset:12
	s_mov_b64 exec, -1
	v_cvt_pk_bf16_f32 v20, v154, v158
	v_cvt_pk_bf16_f32 v21, v162, v166
	v_cvt_pk_bf16_f32 v22, v170, v174
	v_cvt_pk_bf16_f32 v23, v178, v182
	global_store_dwordx4 v3, v[20:23], s[2:3]
	v_cvt_pk_bf16_f32 v24, v186, v190
	v_cvt_pk_bf16_f32 v25, v194, v198
	v_cvt_pk_bf16_f32 v26, v130, v134
	v_cvt_pk_bf16_f32 v27, v138, v142
	global_store_dwordx4 v3, v[24:27], s[2:3] offset:16
	v_lshlrev_b32_e32 v19, 16, v20
	v_and_b32_e32 v114, 0xffff0000, v20
	v_add_f32_e32 v114, v19, v114
	v_lshlrev_b32_e32 v19, 16, v21
	v_and_b32_e32 v115, 0xffff0000, v21
	v_add_f32_e32 v115, v19, v115
	v_lshlrev_b32_e32 v19, 16, v22
	v_and_b32_e32 v116, 0xffff0000, v22
	v_add_f32_e32 v116, v19, v116
	v_lshlrev_b32_e32 v19, 16, v23
	v_and_b32_e32 v117, 0xffff0000, v23
	v_add_f32_e32 v117, v19, v117
	v_lshlrev_b32_e32 v19, 16, v24
	v_and_b32_e32 v118, 0xffff0000, v24
	v_add_f32_e32 v118, v19, v118
	v_lshlrev_b32_e32 v19, 16, v25
	v_and_b32_e32 v119, 0xffff0000, v25
	v_add_f32_e32 v119, v19, v119
	v_lshlrev_b32_e32 v19, 16, v26
	v_and_b32_e32 v120, 0xffff0000, v26
	v_add_f32_e32 v120, v19, v120
	v_lshlrev_b32_e32 v19, 16, v27
	v_and_b32_e32 v121, 0xffff0000, v27
	v_add_f32_e32 v121, v19, v121
	v_add_f32_e32 v114, v114, v115
	v_add_f32_e32 v116, v116, v117
	v_add_f32_e32 v118, v118, v119
	v_add_f32_e32 v120, v120, v121
	v_add_f32_e32 v114, v114, v116
	v_add_f32_e32 v118, v118, v120
	v_add_f32_e32 v110, v114, v118
	s_add_u32 s2, s2, 0x1000
	s_addc_u32 s3, s3, 0
	v_cvt_pk_bf16_f32 v28, v155, v159
	v_cvt_pk_bf16_f32 v29, v163, v167
	v_cvt_pk_bf16_f32 v30, v171, v175
	v_cvt_pk_bf16_f32 v31, v179, v183
	global_store_dwordx4 v3, v[28:31], s[2:3]
	v_cvt_pk_bf16_f32 v32, v187, v191
	v_cvt_pk_bf16_f32 v33, v195, v199
	v_cvt_pk_bf16_f32 v34, v131, v135
	v_cvt_pk_bf16_f32 v35, v139, v143
	global_store_dwordx4 v3, v[32:35], s[2:3] offset:16
	v_lshlrev_b32_e32 v19, 16, v28
	v_and_b32_e32 v114, 0xffff0000, v28
	v_add_f32_e32 v114, v19, v114
	v_lshlrev_b32_e32 v19, 16, v29
	v_and_b32_e32 v115, 0xffff0000, v29
	v_add_f32_e32 v115, v19, v115
	v_lshlrev_b32_e32 v19, 16, v30
	v_and_b32_e32 v116, 0xffff0000, v30
	v_add_f32_e32 v116, v19, v116
	v_lshlrev_b32_e32 v19, 16, v31
	v_and_b32_e32 v117, 0xffff0000, v31
	v_add_f32_e32 v117, v19, v117
	v_lshlrev_b32_e32 v19, 16, v32
	v_and_b32_e32 v118, 0xffff0000, v32
	v_add_f32_e32 v118, v19, v118
	v_lshlrev_b32_e32 v19, 16, v33
	v_and_b32_e32 v119, 0xffff0000, v33
	v_add_f32_e32 v119, v19, v119
	v_lshlrev_b32_e32 v19, 16, v34
	v_and_b32_e32 v120, 0xffff0000, v34
	v_add_f32_e32 v120, v19, v120
	v_lshlrev_b32_e32 v19, 16, v35
	v_and_b32_e32 v121, 0xffff0000, v35
	v_add_f32_e32 v121, v19, v121
	v_add_f32_e32 v114, v114, v115
	v_add_f32_e32 v116, v116, v117
	v_add_f32_e32 v118, v118, v119
	v_add_f32_e32 v120, v120, v121
	v_add_f32_e32 v114, v114, v116
	v_add_f32_e32 v118, v118, v120
	v_add_f32_e32 v111, v114, v118
	s_add_u32 s2, s2, 0x1000
	s_addc_u32 s3, s3, 0
	v_cvt_pk_bf16_f32 v36, v156, v160
	v_cvt_pk_bf16_f32 v37, v164, v168
	v_cvt_pk_bf16_f32 v38, v172, v176
	v_cvt_pk_bf16_f32 v39, v180, v184
	global_store_dwordx4 v3, v[36:39], s[2:3]
	v_cvt_pk_bf16_f32 v40, v188, v192
	v_cvt_pk_bf16_f32 v41, v196, v200
	v_cvt_pk_bf16_f32 v42, v132, v136
	v_cvt_pk_bf16_f32 v43, v140, v144
	global_store_dwordx4 v3, v[40:43], s[2:3] offset:16
	v_lshlrev_b32_e32 v19, 16, v36
	v_and_b32_e32 v114, 0xffff0000, v36
	v_add_f32_e32 v114, v19, v114
	v_lshlrev_b32_e32 v19, 16, v37
	v_and_b32_e32 v115, 0xffff0000, v37
	v_add_f32_e32 v115, v19, v115
	v_lshlrev_b32_e32 v19, 16, v38
	v_and_b32_e32 v116, 0xffff0000, v38
	v_add_f32_e32 v116, v19, v116
	v_lshlrev_b32_e32 v19, 16, v39
	v_and_b32_e32 v117, 0xffff0000, v39
	v_add_f32_e32 v117, v19, v117
	v_lshlrev_b32_e32 v19, 16, v40
	v_and_b32_e32 v118, 0xffff0000, v40
	v_add_f32_e32 v118, v19, v118
	v_lshlrev_b32_e32 v19, 16, v41
	v_and_b32_e32 v119, 0xffff0000, v41
	v_add_f32_e32 v119, v19, v119
	v_lshlrev_b32_e32 v19, 16, v42
	v_and_b32_e32 v120, 0xffff0000, v42
	v_add_f32_e32 v120, v19, v120
	v_lshlrev_b32_e32 v19, 16, v43
	v_and_b32_e32 v121, 0xffff0000, v43
	v_add_f32_e32 v121, v19, v121
	v_add_f32_e32 v114, v114, v115
	v_add_f32_e32 v116, v116, v117
	v_add_f32_e32 v118, v118, v119
	v_add_f32_e32 v120, v120, v121
	v_add_f32_e32 v114, v114, v116
	v_add_f32_e32 v118, v118, v120
	v_add_f32_e32 v112, v114, v118
	s_add_u32 s2, s2, 0x1000
	s_addc_u32 s3, s3, 0
	v_cvt_pk_bf16_f32 v20, v157, v161
	v_cvt_pk_bf16_f32 v21, v165, v169
	v_cvt_pk_bf16_f32 v22, v173, v177
	v_cvt_pk_bf16_f32 v23, v181, v185
	global_store_dwordx4 v3, v[20:23], s[2:3]
	v_cvt_pk_bf16_f32 v24, v189, v193
	v_cvt_pk_bf16_f32 v25, v197, v201
	v_cvt_pk_bf16_f32 v26, v133, v137
	v_cvt_pk_bf16_f32 v27, v141, v145
	global_store_dwordx4 v3, v[24:27], s[2:3] offset:16
	v_lshlrev_b32_e32 v19, 16, v20
	v_and_b32_e32 v114, 0xffff0000, v20
	v_add_f32_e32 v114, v19, v114
	v_lshlrev_b32_e32 v19, 16, v21
	v_and_b32_e32 v115, 0xffff0000, v21
	v_add_f32_e32 v115, v19, v115
	v_lshlrev_b32_e32 v19, 16, v22
	v_and_b32_e32 v116, 0xffff0000, v22
	v_add_f32_e32 v116, v19, v116
	v_lshlrev_b32_e32 v19, 16, v23
	v_and_b32_e32 v117, 0xffff0000, v23
	v_add_f32_e32 v117, v19, v117
	v_lshlrev_b32_e32 v19, 16, v24
	v_and_b32_e32 v118, 0xffff0000, v24
	v_add_f32_e32 v118, v19, v118
	v_lshlrev_b32_e32 v19, 16, v25
	v_and_b32_e32 v119, 0xffff0000, v25
	v_add_f32_e32 v119, v19, v119
	v_lshlrev_b32_e32 v19, 16, v26
	v_and_b32_e32 v120, 0xffff0000, v26
	v_add_f32_e32 v120, v19, v120
	v_lshlrev_b32_e32 v19, 16, v27
	v_and_b32_e32 v121, 0xffff0000, v27
	v_add_f32_e32 v121, v19, v121
	v_add_f32_e32 v114, v114, v115
	v_add_f32_e32 v116, v116, v117
	v_add_f32_e32 v118, v118, v119
	v_add_f32_e32 v120, v120, v121
	v_add_f32_e32 v114, v114, v116
	v_add_f32_e32 v118, v118, v120
	v_add_f32_e32 v113, v114, v118
	ds_bpermute_b32 v106, v48, v110
	ds_bpermute_b32 v107, v48, v111
	ds_bpermute_b32 v108, v48, v112
	ds_bpermute_b32 v109, v48, v113
	s_waitcnt lgkmcnt(0)
	v_add_f32_e32 v110, v110, v106
	v_add_f32_e32 v111, v111, v107
	v_add_f32_e32 v112, v112, v108
	v_add_f32_e32 v113, v113, v109
	ds_bpermute_b32 v106, v1, v110
	ds_bpermute_b32 v107, v1, v111
	ds_bpermute_b32 v108, v1, v112
	ds_bpermute_b32 v109, v1, v113
	s_waitcnt lgkmcnt(0)
	v_add_f32_e32 v110, v110, v106
	v_add_f32_e32 v111, v111, v107
	v_add_f32_e32 v112, v112, v108
	v_add_f32_e32 v113, v113, v109
	s_mov_b64 exec, s[36:37]
	global_atomic_add_f32 v2, v110, s[72:73] offset:0
	global_atomic_add_f32 v2, v111, s[72:73] offset:4
	global_atomic_add_f32 v2, v112, s[72:73] offset:8
	global_atomic_add_f32 v2, v113, s[72:73] offset:12
	s_mov_b64 exec, -1
	v_mul_f32_e32 v98, v204, v82
	v_mul_f32_e32 v99, v205, v82
	v_mul_f32_e32 v100, v206, v82
	v_mul_f32_e32 v101, v207, v82
	v_mul_f32_e32 v204, v204, v66
	v_mul_f32_e32 v205, v205, v66
	v_mul_f32_e32 v206, v206, v66
	v_mul_f32_e32 v207, v207, v66
	v_fmac_f32_e32 v98, v208, v83
	v_fmac_f32_e32 v99, v209, v83
	v_fmac_f32_e32 v100, v210, v83
	v_fmac_f32_e32 v101, v211, v83
	v_mul_f32_e32 v208, v208, v67
	v_mul_f32_e32 v209, v209, v67
	v_mul_f32_e32 v210, v210, v67
	v_mul_f32_e32 v211, v211, v67
	v_fmac_f32_e32 v98, v212, v84
	v_fmac_f32_e32 v99, v213, v84
	v_fmac_f32_e32 v100, v214, v84
	v_fmac_f32_e32 v101, v215, v84
	v_mul_f32_e32 v212, v212, v68
	v_mul_f32_e32 v213, v213, v68
	v_mul_f32_e32 v214, v214, v68
	v_mul_f32_e32 v215, v215, v68
	v_fmac_f32_e32 v98, v216, v85
	v_fmac_f32_e32 v99, v217, v85
	v_fmac_f32_e32 v100, v218, v85
	v_fmac_f32_e32 v101, v219, v85
	v_mul_f32_e32 v216, v216, v69
	v_mul_f32_e32 v217, v217, v69
	v_mul_f32_e32 v218, v218, v69
	v_mul_f32_e32 v219, v219, v69
	v_fmac_f32_e32 v98, v220, v86
	v_fmac_f32_e32 v99, v221, v86
	v_fmac_f32_e32 v100, v222, v86
	v_fmac_f32_e32 v101, v223, v86
	v_mul_f32_e32 v220, v220, v70
	v_mul_f32_e32 v221, v221, v70
	v_mul_f32_e32 v222, v222, v70
	v_mul_f32_e32 v223, v223, v70
	v_fmac_f32_e32 v98, v224, v87
	v_fmac_f32_e32 v99, v225, v87
	v_fmac_f32_e32 v100, v226, v87
	v_fmac_f32_e32 v101, v227, v87
	v_mul_f32_e32 v224, v224, v71
	v_mul_f32_e32 v225, v225, v71
	v_mul_f32_e32 v226, v226, v71
	v_mul_f32_e32 v227, v227, v71
	v_fmac_f32_e32 v98, v228, v88
	v_fmac_f32_e32 v99, v229, v88
	v_fmac_f32_e32 v100, v230, v88
	v_fmac_f32_e32 v101, v231, v88
	v_mul_f32_e32 v228, v228, v72
	v_mul_f32_e32 v229, v229, v72
	v_mul_f32_e32 v230, v230, v72
	v_mul_f32_e32 v231, v231, v72
	v_fmac_f32_e32 v98, v232, v89
	v_fmac_f32_e32 v99, v233, v89
	v_fmac_f32_e32 v100, v234, v89
	v_fmac_f32_e32 v101, v235, v89
	v_mul_f32_e32 v232, v232, v73
	v_mul_f32_e32 v233, v233, v73
	v_mul_f32_e32 v234, v234, v73
	v_mul_f32_e32 v235, v235, v73
	v_fmac_f32_e32 v98, v236, v90
	v_fmac_f32_e32 v99, v237, v90
	v_fmac_f32_e32 v100, v238, v90
	v_fmac_f32_e32 v101, v239, v90
	v_mul_f32_e32 v236, v236, v74
	v_mul_f32_e32 v237, v237, v74
	v_mul_f32_e32 v238, v238, v74
	v_mul_f32_e32 v239, v239, v74
	v_fmac_f32_e32 v98, v240, v91
	v_fmac_f32_e32 v99, v241, v91
	v_fmac_f32_e32 v100, v242, v91
	v_fmac_f32_e32 v101, v243, v91
	v_mul_f32_e32 v240, v240, v75
	v_mul_f32_e32 v241, v241, v75
	v_mul_f32_e32 v242, v242, v75
	v_mul_f32_e32 v243, v243, v75
	v_fmac_f32_e32 v98, v244, v92
	v_fmac_f32_e32 v99, v245, v92
	v_fmac_f32_e32 v100, v246, v92
	v_fmac_f32_e32 v101, v247, v92
	v_mul_f32_e32 v244, v244, v76
	v_mul_f32_e32 v245, v245, v76
	v_mul_f32_e32 v246, v246, v76
	v_mul_f32_e32 v247, v247, v76
	v_fmac_f32_e32 v98, v248, v93
	v_fmac_f32_e32 v99, v249, v93
	v_fmac_f32_e32 v100, v250, v93
	v_fmac_f32_e32 v101, v251, v93
	v_mul_f32_e32 v248, v248, v77
	v_mul_f32_e32 v249, v249, v77
	v_mul_f32_e32 v250, v250, v77
	v_mul_f32_e32 v251, v251, v77
	v_fmac_f32_e32 v98, v50, v94
	v_fmac_f32_e32 v99, v51, v94
	v_fmac_f32_e32 v100, v52, v94
	v_fmac_f32_e32 v101, v53, v94
	v_mul_f32_e32 v50, v50, v78
	v_mul_f32_e32 v51, v51, v78
	v_mul_f32_e32 v52, v52, v78
	v_mul_f32_e32 v53, v53, v78
	v_fmac_f32_e32 v98, v54, v95
	v_fmac_f32_e32 v99, v55, v95
	v_fmac_f32_e32 v100, v56, v95
	v_fmac_f32_e32 v101, v57, v95
	v_mul_f32_e32 v54, v54, v79
	v_mul_f32_e32 v55, v55, v79
	v_mul_f32_e32 v56, v56, v79
	v_mul_f32_e32 v57, v57, v79
	v_fmac_f32_e32 v98, v58, v96
	v_fmac_f32_e32 v99, v59, v96
	v_fmac_f32_e32 v100, v60, v96
	v_fmac_f32_e32 v101, v61, v96
	v_mul_f32_e32 v58, v58, v80
	v_mul_f32_e32 v59, v59, v80
	v_mul_f32_e32 v60, v60, v80
	v_mul_f32_e32 v61, v61, v80
	v_fmac_f32_e32 v98, v62, v97
	v_fmac_f32_e32 v99, v63, v97
	v_fmac_f32_e32 v100, v64, v97
	v_fmac_f32_e32 v101, v65, v97
	v_mul_f32_e32 v62, v62, v81
	v_mul_f32_e32 v63, v63, v81
	v_mul_f32_e32 v64, v64, v81
	v_mul_f32_e32 v65, v65, v81
	v_lshlrev_b32_e32 v2, 2, v125
	v_lshlrev_b32_e32 v3, 12, v125
	v_lshl_add_u32 v3, v7, 1, v3
	ds_bpermute_b32 v106, v48, v98
	ds_bpermute_b32 v107, v48, v99
	ds_bpermute_b32 v108, v48, v100
	ds_bpermute_b32 v109, v48, v101
	s_waitcnt lgkmcnt(0)
	v_add_f32_e32 v98, v98, v106
	v_add_f32_e32 v99, v99, v107
	v_add_f32_e32 v100, v100, v108
	v_add_f32_e32 v101, v101, v109
	ds_bpermute_b32 v106, v1, v98
	ds_bpermute_b32 v107, v1, v99
	ds_bpermute_b32 v108, v1, v100
	ds_bpermute_b32 v109, v1, v101
	s_waitcnt lgkmcnt(0)
	v_add_f32_e32 v98, v98, v106
	v_add_f32_e32 v99, v99, v107
	v_add_f32_e32 v100, v100, v108
	v_add_f32_e32 v101, v101, v109
	s_mov_b64 exec, s[36:37]
	global_atomic_add_f32 v2, v98, s[78:79] offset:0
	global_atomic_add_f32 v2, v99, s[78:79] offset:4
	global_atomic_add_f32 v2, v100, s[78:79] offset:8
	global_atomic_add_f32 v2, v101, s[78:79] offset:12
	s_mov_b64 exec, -1
	v_cvt_pk_bf16_f32 v20, v204, v208
	v_cvt_pk_bf16_f32 v21, v212, v216
	v_cvt_pk_bf16_f32 v22, v220, v224
	v_cvt_pk_bf16_f32 v23, v228, v232
	global_store_dwordx4 v3, v[20:23], s[4:5]
	v_cvt_pk_bf16_f32 v24, v236, v240
	v_cvt_pk_bf16_f32 v25, v244, v248
	v_cvt_pk_bf16_f32 v26, v50, v54
	v_cvt_pk_bf16_f32 v27, v58, v62
	global_store_dwordx4 v3, v[24:27], s[4:5] offset:16
	v_lshlrev_b32_e32 v19, 16, v20
	v_and_b32_e32 v114, 0xffff0000, v20
	v_add_f32_e32 v114, v19, v114
	v_lshlrev_b32_e32 v19, 16, v21
	v_and_b32_e32 v115, 0xffff0000, v21
	v_add_f32_e32 v115, v19, v115
	v_lshlrev_b32_e32 v19, 16, v22
	v_and_b32_e32 v116, 0xffff0000, v22
	v_add_f32_e32 v116, v19, v116
	v_lshlrev_b32_e32 v19, 16, v23
	v_and_b32_e32 v117, 0xffff0000, v23
	v_add_f32_e32 v117, v19, v117
	v_lshlrev_b32_e32 v19, 16, v24
	v_and_b32_e32 v118, 0xffff0000, v24
	v_add_f32_e32 v118, v19, v118
	v_lshlrev_b32_e32 v19, 16, v25
	v_and_b32_e32 v119, 0xffff0000, v25
	v_add_f32_e32 v119, v19, v119
	v_lshlrev_b32_e32 v19, 16, v26
	v_and_b32_e32 v120, 0xffff0000, v26
	v_add_f32_e32 v120, v19, v120
	v_lshlrev_b32_e32 v19, 16, v27
	v_and_b32_e32 v121, 0xffff0000, v27
	v_add_f32_e32 v121, v19, v121
	v_add_f32_e32 v114, v114, v115
	v_add_f32_e32 v116, v116, v117
	v_add_f32_e32 v118, v118, v119
	v_add_f32_e32 v120, v120, v121
	v_add_f32_e32 v114, v114, v116
	v_add_f32_e32 v118, v118, v120
	v_add_f32_e32 v110, v114, v118
	s_add_u32 s4, s4, 0x1000
	s_addc_u32 s5, s5, 0
	v_cvt_pk_bf16_f32 v28, v205, v209
	v_cvt_pk_bf16_f32 v29, v213, v217
	v_cvt_pk_bf16_f32 v30, v221, v225
	v_cvt_pk_bf16_f32 v31, v229, v233
	global_store_dwordx4 v3, v[28:31], s[4:5]
	v_cvt_pk_bf16_f32 v32, v237, v241
	v_cvt_pk_bf16_f32 v33, v245, v249
	v_cvt_pk_bf16_f32 v34, v51, v55
	v_cvt_pk_bf16_f32 v35, v59, v63
	global_store_dwordx4 v3, v[32:35], s[4:5] offset:16
	v_lshlrev_b32_e32 v19, 16, v28
	v_and_b32_e32 v114, 0xffff0000, v28
	v_add_f32_e32 v114, v19, v114
	v_lshlrev_b32_e32 v19, 16, v29
	v_and_b32_e32 v115, 0xffff0000, v29
	v_add_f32_e32 v115, v19, v115
	v_lshlrev_b32_e32 v19, 16, v30
	v_and_b32_e32 v116, 0xffff0000, v30
	v_add_f32_e32 v116, v19, v116
	v_lshlrev_b32_e32 v19, 16, v31
	v_and_b32_e32 v117, 0xffff0000, v31
	v_add_f32_e32 v117, v19, v117
	v_lshlrev_b32_e32 v19, 16, v32
	v_and_b32_e32 v118, 0xffff0000, v32
	v_add_f32_e32 v118, v19, v118
	v_lshlrev_b32_e32 v19, 16, v33
	v_and_b32_e32 v119, 0xffff0000, v33
	v_add_f32_e32 v119, v19, v119
	v_lshlrev_b32_e32 v19, 16, v34
	v_and_b32_e32 v120, 0xffff0000, v34
	v_add_f32_e32 v120, v19, v120
	v_lshlrev_b32_e32 v19, 16, v35
	v_and_b32_e32 v121, 0xffff0000, v35
	v_add_f32_e32 v121, v19, v121
	v_add_f32_e32 v114, v114, v115
	v_add_f32_e32 v116, v116, v117
	v_add_f32_e32 v118, v118, v119
	v_add_f32_e32 v120, v120, v121
	v_add_f32_e32 v114, v114, v116
	v_add_f32_e32 v118, v118, v120
	v_add_f32_e32 v111, v114, v118
	s_add_u32 s4, s4, 0x1000
	s_addc_u32 s5, s5, 0
	v_cvt_pk_bf16_f32 v36, v206, v210
	v_cvt_pk_bf16_f32 v37, v214, v218
	v_cvt_pk_bf16_f32 v38, v222, v226
	v_cvt_pk_bf16_f32 v39, v230, v234
	global_store_dwordx4 v3, v[36:39], s[4:5]
	v_cvt_pk_bf16_f32 v40, v238, v242
	v_cvt_pk_bf16_f32 v41, v246, v250
	v_cvt_pk_bf16_f32 v42, v52, v56
	v_cvt_pk_bf16_f32 v43, v60, v64
	global_store_dwordx4 v3, v[40:43], s[4:5] offset:16
	v_lshlrev_b32_e32 v19, 16, v36
	v_and_b32_e32 v114, 0xffff0000, v36
	v_add_f32_e32 v114, v19, v114
	v_lshlrev_b32_e32 v19, 16, v37
	v_and_b32_e32 v115, 0xffff0000, v37
	v_add_f32_e32 v115, v19, v115
	v_lshlrev_b32_e32 v19, 16, v38
	v_and_b32_e32 v116, 0xffff0000, v38
	v_add_f32_e32 v116, v19, v116
	v_lshlrev_b32_e32 v19, 16, v39
	v_and_b32_e32 v117, 0xffff0000, v39
	v_add_f32_e32 v117, v19, v117
	v_lshlrev_b32_e32 v19, 16, v40
	v_and_b32_e32 v118, 0xffff0000, v40
	v_add_f32_e32 v118, v19, v118
	v_lshlrev_b32_e32 v19, 16, v41
	v_and_b32_e32 v119, 0xffff0000, v41
	v_add_f32_e32 v119, v19, v119
	v_lshlrev_b32_e32 v19, 16, v42
	v_and_b32_e32 v120, 0xffff0000, v42
	v_add_f32_e32 v120, v19, v120
	v_lshlrev_b32_e32 v19, 16, v43
	v_and_b32_e32 v121, 0xffff0000, v43
	v_add_f32_e32 v121, v19, v121
	v_add_f32_e32 v114, v114, v115
	v_add_f32_e32 v116, v116, v117
	v_add_f32_e32 v118, v118, v119
	v_add_f32_e32 v120, v120, v121
	v_add_f32_e32 v114, v114, v116
	v_add_f32_e32 v118, v118, v120
	v_add_f32_e32 v112, v114, v118
	s_add_u32 s4, s4, 0x1000
	s_addc_u32 s5, s5, 0
	v_cvt_pk_bf16_f32 v20, v207, v211
	v_cvt_pk_bf16_f32 v21, v215, v219
	v_cvt_pk_bf16_f32 v22, v223, v227
	v_cvt_pk_bf16_f32 v23, v231, v235
	global_store_dwordx4 v3, v[20:23], s[4:5]
	v_cvt_pk_bf16_f32 v24, v239, v243
	v_cvt_pk_bf16_f32 v25, v247, v251
	v_cvt_pk_bf16_f32 v26, v53, v57
	v_cvt_pk_bf16_f32 v27, v61, v65
	global_store_dwordx4 v3, v[24:27], s[4:5] offset:16
	v_lshlrev_b32_e32 v19, 16, v20
	v_and_b32_e32 v114, 0xffff0000, v20
	v_add_f32_e32 v114, v19, v114
	v_lshlrev_b32_e32 v19, 16, v21
	v_and_b32_e32 v115, 0xffff0000, v21
	v_add_f32_e32 v115, v19, v115
	v_lshlrev_b32_e32 v19, 16, v22
	v_and_b32_e32 v116, 0xffff0000, v22
	v_add_f32_e32 v116, v19, v116
	v_lshlrev_b32_e32 v19, 16, v23
	v_and_b32_e32 v117, 0xffff0000, v23
	v_add_f32_e32 v117, v19, v117
	v_lshlrev_b32_e32 v19, 16, v24
	v_and_b32_e32 v118, 0xffff0000, v24
	v_add_f32_e32 v118, v19, v118
	v_lshlrev_b32_e32 v19, 16, v25
	v_and_b32_e32 v119, 0xffff0000, v25
	v_add_f32_e32 v119, v19, v119
	v_lshlrev_b32_e32 v19, 16, v26
	v_and_b32_e32 v120, 0xffff0000, v26
	v_add_f32_e32 v120, v19, v120
	v_lshlrev_b32_e32 v19, 16, v27
	v_and_b32_e32 v121, 0xffff0000, v27
	v_add_f32_e32 v121, v19, v121
	v_add_f32_e32 v114, v114, v115
	v_add_f32_e32 v116, v116, v117
	v_add_f32_e32 v118, v118, v119
	v_add_f32_e32 v120, v120, v121
	v_add_f32_e32 v114, v114, v116
	v_add_f32_e32 v118, v118, v120
	v_add_f32_e32 v113, v114, v118
	ds_bpermute_b32 v106, v48, v110
	ds_bpermute_b32 v107, v48, v111
	ds_bpermute_b32 v108, v48, v112
	ds_bpermute_b32 v109, v48, v113
	s_waitcnt lgkmcnt(0)
	v_add_f32_e32 v110, v110, v106
	v_add_f32_e32 v111, v111, v107
	v_add_f32_e32 v112, v112, v108
	v_add_f32_e32 v113, v113, v109
	ds_bpermute_b32 v106, v1, v110
	ds_bpermute_b32 v107, v1, v111
	ds_bpermute_b32 v108, v1, v112
	ds_bpermute_b32 v109, v1, v113
	s_waitcnt lgkmcnt(0)
	v_add_f32_e32 v110, v110, v106
	v_add_f32_e32 v111, v111, v107
	v_add_f32_e32 v112, v112, v108
	v_add_f32_e32 v113, v113, v109
	s_mov_b64 exec, s[36:37]
	global_atomic_add_f32 v2, v110, s[76:77] offset:0
	global_atomic_add_f32 v2, v111, s[76:77] offset:4
	global_atomic_add_f32 v2, v112, s[76:77] offset:8
	global_atomic_add_f32 v2, v113, s[76:77] offset:12
	s_mov_b64 exec, -1
	s_waitcnt vmcnt(16)
	s_branch .Lw1d_loop
.Lw1d_rest:
	v_lshlrev_b32_e32 v2, 4, v0
	v_add_u32_e32 v3, 0x10000, v2
	ds_read_b128 v[66:69], v2 offset:0
	ds_read_b128 v[70:73], v2 offset:8192
	ds_read_b128 v[74:77], v2 offset:16384
	ds_read_b128 v[78:81], v2 offset:24576
	ds_read_b128 v[82:85], v2 offset:32768
	ds_read_b128 v[86:89], v2 offset:40960
	ds_read_b128 v[90:93], v2 offset:49152
	ds_read_b128 v[94:97], v2 offset:57344
	ds_read_b128 v[98:101], v3 offset:0
	ds_read_b128 v[102:105], v3 offset:8192
	ds_read_b128 v[106:109], v3 offset:16384
	ds_read_b128 v[110:113], v3 offset:24576
	ds_read_b128 v[114:117], v3 offset:32768
	ds_read_b128 v[118:121], v3 offset:40960
	ds_read_b128 v[122:125], v3 offset:49152
	ds_read_b128 v[126:129], v3 offset:57344
	s_waitcnt lgkmcnt(0)

.LBB0_1229:
	s_or_b64 exec, exec, s[0:1]
	s_waitcnt lgkmcnt(0)
	s_barrier
	ds_read_b32 v1, v155
	s_movk_i32 s0, 0x61f
	s_waitcnt lgkmcnt(0)
	v_add_u32_e32 v1, s98, v1
	v_cmp_lt_u32_e32 vcc, s0, v1
	v_readfirstlane_b32 s42, v1
	s_mov_b64 s[0:1], -1
	s_cbranch_vccnz .LBB0_1224
	s_cmpk_gt_u32 s42, 0x2ff
	s_cbranch_scc1 .Lq_nomap
	s_cmpk_lt_u32 s42, 0xc0
	s_cbranch_scc1 .Lq_nomap
	s_cmpk_lt_u32 s42, 0x2c0
	s_cbranch_scc1 .Lq_g1
	s_sub_u32 s42, s42, 0x200
	s_branch .Lq_nomap
